# Hyena: A-fragment LDS reads from one base register with immediate offsets; 32-bit multiply-add for the B row address
# speedup vs baseline: 1.0067x; 1.0067x over previous
; __device__ __forceinline__ void hyena_item(const Ctx& C, ArgsP a, int ly, int c, bf16_t* yout) {
;     ...
;             for (int dd = 0; dd < DG; ++dd) { const int d = dlo + dd; if (d == -64) continue;
;                 const bf16_t* Wd = Wb + abase + 128 * (DG - 1 - dd);
;                 bf16x8 fa[10];
; #pragma unroll
;                 for (int q = 0; q < 10; ++q) fa[q] = *(const bf16x8*)(Wd + 16 * (q - 3));
.LBB0_854:
	s_cmp_eq_u32 s59, s56
	s_cbranch_scc1 .LBB0_853
	s_waitcnt lgkmcnt(1)
	v_add_u32_e32 v78, s56, v1
	v_add_u32_e32 v211, 0x1a7a0, v78
	ds_read_b128 v[98:101], v211 offset:32
	ds_read_b128 v[90:93], v211 offset:64
	ds_read_b128 v[102:105], v211
	ds_read_b128 v[94:97], v211 offset:96
	ds_read_b128 v[74:77], v211 offset:128
	ds_read_b128 v[82:85], v211 offset:160
	s_waitcnt lgkmcnt(6)
	ds_read_b128 v[66:69], v211 offset:192
	ds_read_b128 v[70:73], v211 offset:224
	ds_read_b128 v[78:81], v211 offset:256
	ds_read_b128 v[86:89], v211 offset:288
	s_sub_i32 s6, s57, 47
	s_cmp_gt_i32 s6, 15
	v_add_u32_e32 v210, s73, v142
	s_cbranch_scc0 .LBB0_859
	s_cmpk_gt_u32 s57, 0x4e
	s_cbranch_scc0 .LBB0_860

; __device__ __forceinline__ void hyena_item(const Ctx& C, ArgsP a, int ly, int c, bf16_t* yout) {
;     ...
;                 if (d <= 15) HY_MMA(0)
.LBB0_859:
	v_add_co_u32_e32 v211, vcc, 64, v210
	s_nop 1
	v_cndmask_b32_e32 v211, 0, v211, vcc
	v_add_u32_e32 v211, s80, v211
	v_mad_u32_u24 v224, v211, s78, v108
	ds_read_b128 v[212:215], v224
	ds_read_b128 v[216:219], v224 offset:64
	ds_read_b128 v[220:223], v224 offset:128
	ds_read_b128 v[224:227], v224 offset:192
	s_setprio 1
	s_cmp_eq_u64 vcc, exec
	s_cbranch_scc1 .Lhy_fast_859
	s_waitcnt lgkmcnt(3)
	v_cndmask_b32_e32 v215, 0, v215, vcc
	v_cndmask_b32_e32 v214, 0, v214, vcc
	v_cndmask_b32_e32 v213, 0, v213, vcc
	v_cndmask_b32_e32 v212, 0, v212, vcc
	s_nop 1
	v_mfma_f32_16x16x32_bf16 v[62:65], v[94:97], v[212:215], v[62:65]
	v_mfma_f32_16x16x32_bf16 v[58:61], v[90:93], v[212:215], v[58:61]
	v_mfma_f32_16x16x32_bf16 v[54:57], v[98:101], v[212:215], v[54:57]
	v_mfma_f32_16x16x32_bf16 v[50:53], v[102:105], v[212:215], v[50:53]
	s_waitcnt lgkmcnt(2)
	v_cndmask_b32_e32 v215, 0, v219, vcc
	v_cndmask_b32_e32 v214, 0, v218, vcc
	v_cndmask_b32_e32 v213, 0, v217, vcc
	v_cndmask_b32_e32 v212, 0, v216, vcc
	s_nop 1
	v_mfma_f32_16x16x32_bf16 v[62:65], v[82:85], v[212:215], v[62:65]
	v_mfma_f32_16x16x32_bf16 v[58:61], v[74:77], v[212:215], v[58:61]
	v_mfma_f32_16x16x32_bf16 v[54:57], v[94:97], v[212:215], v[54:57]
	v_mfma_f32_16x16x32_bf16 v[50:53], v[90:93], v[212:215], v[50:53]
	s_waitcnt lgkmcnt(1)
	v_cndmask_b32_e32 v215, 0, v223, vcc
	v_cndmask_b32_e32 v214, 0, v222, vcc
	v_cndmask_b32_e32 v213, 0, v221, vcc
	v_cndmask_b32_e32 v212, 0, v220, vcc
	s_nop 1
	v_mfma_f32_16x16x32_bf16 v[62:65], v[70:73], v[212:215], v[62:65]
	v_mfma_f32_16x16x32_bf16 v[58:61], v[66:69], v[212:215], v[58:61]
	v_mfma_f32_16x16x32_bf16 v[54:57], v[82:85], v[212:215], v[54:57]
	v_mfma_f32_16x16x32_bf16 v[50:53], v[74:77], v[212:215], v[50:53]
	s_waitcnt lgkmcnt(0)
	v_cndmask_b32_e32 v215, 0, v227, vcc
	v_cndmask_b32_e32 v214, 0, v226, vcc
	v_cndmask_b32_e32 v213, 0, v225, vcc
	v_cndmask_b32_e32 v212, 0, v224, vcc
	s_nop 1
	v_mfma_f32_16x16x32_bf16 v[62:65], v[86:89], v[212:215], v[62:65]
	v_mfma_f32_16x16x32_bf16 v[58:61], v[78:81], v[212:215], v[58:61]
	v_mfma_f32_16x16x32_bf16 v[54:57], v[70:73], v[212:215], v[54:57]
	v_mfma_f32_16x16x32_bf16 v[50:53], v[66:69], v[212:215], v[50:53]
	s_setprio 0

; __device__ __forceinline__ void hyena_item(const Ctx& C, ArgsP a, int ly, int c, bf16_t* yout) {
;     ...
;                 if (d >= -47 && d <= 31) HY_MMA(1)
.LBB0_860:
	v_add_u32_e32 v211, 0x50, v210
	v_cmp_gt_u32_e32 vcc, 64, v211
	s_nop 1
	v_cndmask_b32_e32 v211, 0, v211, vcc
	v_add_u32_e32 v211, s80, v211
	v_mad_u32_u24 v224, v211, s78, v108
	ds_read_b128 v[212:215], v224
	ds_read_b128 v[216:219], v224 offset:64
	ds_read_b128 v[220:223], v224 offset:128
	ds_read_b128 v[224:227], v224 offset:192
	s_setprio 1
	s_cmp_eq_u64 vcc, exec
	s_cbranch_scc1 .Lhy_fast_860
	s_waitcnt lgkmcnt(3)
	v_cndmask_b32_e32 v215, 0, v215, vcc
	v_cndmask_b32_e32 v214, 0, v214, vcc
	v_cndmask_b32_e32 v213, 0, v213, vcc
	v_cndmask_b32_e32 v212, 0, v212, vcc
	s_nop 1
	v_mfma_f32_16x16x32_bf16 v[46:49], v[94:97], v[212:215], v[46:49]
	v_mfma_f32_16x16x32_bf16 v[42:45], v[90:93], v[212:215], v[42:45]
	v_mfma_f32_16x16x32_bf16 v[38:41], v[98:101], v[212:215], v[38:41]
	v_mfma_f32_16x16x32_bf16 v[34:37], v[102:105], v[212:215], v[34:37]
	s_waitcnt lgkmcnt(2)
	v_cndmask_b32_e32 v215, 0, v219, vcc
	v_cndmask_b32_e32 v214, 0, v218, vcc
	v_cndmask_b32_e32 v213, 0, v217, vcc
	v_cndmask_b32_e32 v212, 0, v216, vcc
	s_nop 1
	v_mfma_f32_16x16x32_bf16 v[46:49], v[82:85], v[212:215], v[46:49]
	v_mfma_f32_16x16x32_bf16 v[42:45], v[74:77], v[212:215], v[42:45]
	v_mfma_f32_16x16x32_bf16 v[38:41], v[94:97], v[212:215], v[38:41]
	v_mfma_f32_16x16x32_bf16 v[34:37], v[90:93], v[212:215], v[34:37]
	s_waitcnt lgkmcnt(1)
	v_cndmask_b32_e32 v215, 0, v223, vcc
	v_cndmask_b32_e32 v214, 0, v222, vcc
	v_cndmask_b32_e32 v213, 0, v221, vcc
	v_cndmask_b32_e32 v212, 0, v220, vcc
	s_nop 1
	v_mfma_f32_16x16x32_bf16 v[46:49], v[70:73], v[212:215], v[46:49]
	v_mfma_f32_16x16x32_bf16 v[42:45], v[66:69], v[212:215], v[42:45]
	v_mfma_f32_16x16x32_bf16 v[38:41], v[82:85], v[212:215], v[38:41]
	v_mfma_f32_16x16x32_bf16 v[34:37], v[74:77], v[212:215], v[34:37]
	s_waitcnt lgkmcnt(0)
	v_cndmask_b32_e32 v215, 0, v227, vcc
	v_cndmask_b32_e32 v214, 0, v226, vcc
	v_cndmask_b32_e32 v213, 0, v225, vcc
	v_cndmask_b32_e32 v212, 0, v224, vcc
	s_nop 1
	v_mfma_f32_16x16x32_bf16 v[46:49], v[86:89], v[212:215], v[46:49]
	v_mfma_f32_16x16x32_bf16 v[42:45], v[78:81], v[212:215], v[42:45]
	v_mfma_f32_16x16x32_bf16 v[38:41], v[70:73], v[212:215], v[38:41]
	v_mfma_f32_16x16x32_bf16 v[34:37], v[66:69], v[212:215], v[34:37]
	s_setprio 0

; __device__ __forceinline__ void hyena_item(const Ctx& C, ArgsP a, int ly, int c, bf16_t* yout) {
;     ...
;                 if (d >= -31 && d <= 47) HY_MMA(2)
.LBB0_861:
	v_add_u32_e32 v211, 0x60, v210
	v_cmp_gt_u32_e32 vcc, 64, v211
	s_nop 1
	v_cndmask_b32_e32 v211, 0, v211, vcc
	v_add_u32_e32 v211, s80, v211
	v_mad_u32_u24 v224, v211, s78, v108
	ds_read_b128 v[212:215], v224
	ds_read_b128 v[216:219], v224 offset:64
	ds_read_b128 v[220:223], v224 offset:128
	ds_read_b128 v[224:227], v224 offset:192
	s_setprio 1
	s_cmp_eq_u64 vcc, exec
	s_cbranch_scc1 .Lhy_fast_861
	s_waitcnt lgkmcnt(3)
	v_cndmask_b32_e32 v215, 0, v215, vcc
	v_cndmask_b32_e32 v214, 0, v214, vcc
	v_cndmask_b32_e32 v213, 0, v213, vcc
	v_cndmask_b32_e32 v212, 0, v212, vcc
	s_nop 1
	v_mfma_f32_16x16x32_bf16 v[30:33], v[94:97], v[212:215], v[30:33]
	v_mfma_f32_16x16x32_bf16 v[26:29], v[90:93], v[212:215], v[26:29]
	v_mfma_f32_16x16x32_bf16 v[22:25], v[98:101], v[212:215], v[22:25]
	v_mfma_f32_16x16x32_bf16 v[18:21], v[102:105], v[212:215], v[18:21]
	s_waitcnt lgkmcnt(2)
	v_cndmask_b32_e32 v215, 0, v219, vcc
	v_cndmask_b32_e32 v214, 0, v218, vcc
	v_cndmask_b32_e32 v213, 0, v217, vcc
	v_cndmask_b32_e32 v212, 0, v216, vcc
	s_nop 1
	v_mfma_f32_16x16x32_bf16 v[30:33], v[82:85], v[212:215], v[30:33]
	v_mfma_f32_16x16x32_bf16 v[26:29], v[74:77], v[212:215], v[26:29]
	v_mfma_f32_16x16x32_bf16 v[22:25], v[94:97], v[212:215], v[22:25]
	v_mfma_f32_16x16x32_bf16 v[18:21], v[90:93], v[212:215], v[18:21]
	s_waitcnt lgkmcnt(1)
	v_cndmask_b32_e32 v215, 0, v223, vcc
	v_cndmask_b32_e32 v214, 0, v222, vcc
	v_cndmask_b32_e32 v213, 0, v221, vcc
	v_cndmask_b32_e32 v212, 0, v220, vcc
	s_nop 1
	v_mfma_f32_16x16x32_bf16 v[30:33], v[70:73], v[212:215], v[30:33]
	v_mfma_f32_16x16x32_bf16 v[26:29], v[66:69], v[212:215], v[26:29]
	v_mfma_f32_16x16x32_bf16 v[22:25], v[82:85], v[212:215], v[22:25]
	v_mfma_f32_16x16x32_bf16 v[18:21], v[74:77], v[212:215], v[18:21]
	s_waitcnt lgkmcnt(0)
	v_cndmask_b32_e32 v215, 0, v227, vcc
	v_cndmask_b32_e32 v214, 0, v226, vcc
	v_cndmask_b32_e32 v213, 0, v225, vcc
	v_cndmask_b32_e32 v212, 0, v224, vcc
	s_nop 1
	v_mfma_f32_16x16x32_bf16 v[30:33], v[86:89], v[212:215], v[30:33]
	v_mfma_f32_16x16x32_bf16 v[26:29], v[78:81], v[212:215], v[26:29]
	v_mfma_f32_16x16x32_bf16 v[22:25], v[70:73], v[212:215], v[22:25]
	v_mfma_f32_16x16x32_bf16 v[18:21], v[66:69], v[212:215], v[18:21]
	s_setprio 0

; __device__ __forceinline__ void hyena_item(const Ctx& C, ArgsP a, int ly, int c, bf16_t* yout) {
;     ...
;                 if (d >= -15) HY_MMA(3)
.LBB0_862:
	v_add_u32_e32 v210, 0x70, v210
	v_cmp_gt_u32_e32 vcc, 64, v210
	s_nop 1
	v_cndmask_b32_e32 v210, 0, v210, vcc
	v_add_u32_e32 v210, s80, v210
	v_mad_u32_u24 v222, v210, s78, v108
	ds_read_b128 v[210:213], v222
	ds_read_b128 v[214:217], v222 offset:64
	ds_read_b128 v[218:221], v222 offset:128
	ds_read_b128 v[222:225], v222 offset:192
	s_setprio 1
	s_cmp_eq_u64 vcc, exec
	s_cbranch_scc1 .Lhy_fast_862
	s_waitcnt lgkmcnt(3)
	v_cndmask_b32_e32 v213, 0, v213, vcc
	v_cndmask_b32_e32 v212, 0, v212, vcc
	v_cndmask_b32_e32 v211, 0, v211, vcc
	v_cndmask_b32_e32 v210, 0, v210, vcc
	s_nop 1
	v_mfma_f32_16x16x32_bf16 v[14:17], v[94:97], v[210:213], v[14:17]
	v_mfma_f32_16x16x32_bf16 v[10:13], v[90:93], v[210:213], v[10:13]
	v_mfma_f32_16x16x32_bf16 v[6:9], v[98:101], v[210:213], v[6:9]
	s_waitcnt lgkmcnt(2)
	v_cndmask_b32_e32 v101, 0, v217, vcc
	v_cndmask_b32_e32 v100, 0, v216, vcc
	v_cndmask_b32_e32 v99, 0, v215, vcc
	v_mfma_f32_16x16x32_bf16 v[2:5], v[102:105], v[210:213], v[2:5]
	v_cndmask_b32_e32 v98, 0, v214, vcc
	s_nop 1
	v_mfma_f32_16x16x32_bf16 v[14:17], v[82:85], v[98:101], v[14:17]
	v_mfma_f32_16x16x32_bf16 v[10:13], v[74:77], v[98:101], v[10:13]
	v_mfma_f32_16x16x32_bf16 v[6:9], v[94:97], v[98:101], v[6:9]
	v_mfma_f32_16x16x32_bf16 v[2:5], v[90:93], v[98:101], v[2:5]
	s_waitcnt lgkmcnt(1)
	v_cndmask_b32_e32 v93, 0, v221, vcc
	v_cndmask_b32_e32 v92, 0, v220, vcc
	v_cndmask_b32_e32 v91, 0, v219, vcc
	v_cndmask_b32_e32 v90, 0, v218, vcc
	s_nop 1
	v_mfma_f32_16x16x32_bf16 v[14:17], v[70:73], v[90:93], v[14:17]
	v_mfma_f32_16x16x32_bf16 v[10:13], v[66:69], v[90:93], v[10:13]
	v_mfma_f32_16x16x32_bf16 v[6:9], v[82:85], v[90:93], v[6:9]
	v_mfma_f32_16x16x32_bf16 v[2:5], v[74:77], v[90:93], v[2:5]
	s_waitcnt lgkmcnt(0)
	v_cndmask_b32_e32 v77, 0, v225, vcc
	v_cndmask_b32_e32 v76, 0, v224, vcc
	v_cndmask_b32_e32 v75, 0, v223, vcc
	v_cndmask_b32_e32 v74, 0, v222, vcc
	s_nop 1
	v_mfma_f32_16x16x32_bf16 v[14:17], v[86:89], v[74:77], v[14:17]
	v_mfma_f32_16x16x32_bf16 v[10:13], v[78:81], v[74:77], v[10:13]
	v_mfma_f32_16x16x32_bf16 v[6:9], v[70:73], v[74:77], v[6:9]
	v_mfma_f32_16x16x32_bf16 v[2:5], v[66:69], v[74:77], v[2:5]
	s_setprio 0
